# row-norm phases: the 8 split-K partial-slab loads of each chunk issued together (one wait) instead of a vmcnt(0) after every load
# speedup vs baseline: 1.0215x; 1.0215x over previous
.LBB0_84:
	s_or_saveexec_b64 s[26:27], s[26:27]
	v_add_u32_e32 v24, 0xffffc000, v0
	v_mov_b32_e32 v25, v2
	v_lshlrev_b64 v[24:25], 12, v[24:25]
	v_lshl_add_u64 v[46:47], v[42:43], 0, v[24:25]
	s_xor_b64 exec, exec, s[26:27]
	s_cbranch_execz .LBB0_86
	v_add_co_u32_e32 v84, vcc, 0x400000, v46
	s_nop 1
	v_addc_co_u32_e32 v85, vcc, 0, v47, vcc
	v_add_co_u32_e32 v86, vcc, 0x800000, v46
	s_nop 1
	v_addc_co_u32_e32 v87, vcc, 0, v47, vcc
	v_add_co_u32_e32 v88, vcc, 0xc00000, v46
	s_nop 1
	v_addc_co_u32_e32 v89, vcc, 0, v47, vcc
	v_add_co_u32_e32 v90, vcc, 0x1000000, v46
	s_nop 1
	v_addc_co_u32_e32 v91, vcc, 0, v47, vcc
	v_add_co_u32_e32 v92, vcc, 0x1400000, v46
	s_nop 1
	v_addc_co_u32_e32 v93, vcc, 0, v47, vcc
	v_add_co_u32_e32 v94, vcc, 0x1800000, v46
	s_nop 1
	v_addc_co_u32_e32 v95, vcc, 0, v47, vcc
	v_add_co_u32_e32 v96, vcc, 0x1c00000, v46
	s_nop 1
	v_addc_co_u32_e32 v97, vcc, 0, v47, vcc
	global_load_dwordx4 v[20:23], v[46:47], off
	global_load_dwordx4 v[100:103], v[84:85], off
	global_load_dwordx4 v[104:107], v[86:87], off
	global_load_dwordx4 v[108:111], v[88:89], off
	global_load_dwordx4 v[112:115], v[90:91], off
	global_load_dwordx4 v[116:119], v[92:93], off
	global_load_dwordx4 v[120:123], v[94:95], off
	global_load_dwordx4 v[124:127], v[96:97], off
	s_waitcnt vmcnt(0)
	v_pk_add_f32 v[20:21], v[20:21], v[100:101]
	v_pk_add_f32 v[22:23], v[22:23], v[102:103]
	v_pk_add_f32 v[20:21], v[20:21], v[104:105]
	v_pk_add_f32 v[22:23], v[22:23], v[106:107]
	v_pk_add_f32 v[20:21], v[20:21], v[108:109]
	v_pk_add_f32 v[22:23], v[22:23], v[110:111]
	v_pk_add_f32 v[20:21], v[20:21], v[112:113]
	v_pk_add_f32 v[22:23], v[22:23], v[114:115]
	v_pk_add_f32 v[20:21], v[20:21], v[116:117]
	v_pk_add_f32 v[22:23], v[22:23], v[118:119]
	v_pk_add_f32 v[20:21], v[20:21], v[120:121]
	v_pk_add_f32 v[22:23], v[22:23], v[122:123]
	v_pk_add_f32 v[20:21], v[20:21], v[124:125]
	v_pk_add_f32 v[22:23], v[22:23], v[126:127]

.LBB0_89:
	v_add_co_u32_e32 v84, vcc, 0x400000, v46
	s_nop 1
	v_addc_co_u32_e32 v85, vcc, 0, v47, vcc
	v_add_co_u32_e32 v86, vcc, 0x800000, v46
	s_nop 1
	v_addc_co_u32_e32 v87, vcc, 0, v47, vcc
	v_add_co_u32_e32 v88, vcc, 0xc00000, v46
	s_nop 1
	v_addc_co_u32_e32 v89, vcc, 0, v47, vcc
	v_add_co_u32_e32 v90, vcc, 0x1000000, v46
	s_nop 1
	v_addc_co_u32_e32 v91, vcc, 0, v47, vcc
	v_add_co_u32_e32 v92, vcc, 0x1400000, v46
	s_nop 1
	v_addc_co_u32_e32 v93, vcc, 0, v47, vcc
	v_add_co_u32_e32 v94, vcc, 0x1800000, v46
	s_nop 1
	v_addc_co_u32_e32 v95, vcc, 0, v47, vcc
	v_add_co_u32_e32 v96, vcc, 0x1c00000, v46
	s_nop 1
	v_addc_co_u32_e32 v97, vcc, 0, v47, vcc
	global_load_dwordx4 v[24:27], v[46:47], off offset:1024
	global_load_dwordx4 v[100:103], v[84:85], off offset:1024
	global_load_dwordx4 v[104:107], v[86:87], off offset:1024
	global_load_dwordx4 v[108:111], v[88:89], off offset:1024
	global_load_dwordx4 v[112:115], v[90:91], off offset:1024
	global_load_dwordx4 v[116:119], v[92:93], off offset:1024
	global_load_dwordx4 v[120:123], v[94:95], off offset:1024
	global_load_dwordx4 v[124:127], v[96:97], off offset:1024
	s_waitcnt vmcnt(0)
	v_pk_add_f32 v[24:25], v[24:25], v[100:101]
	v_pk_add_f32 v[26:27], v[26:27], v[102:103]
	v_pk_add_f32 v[24:25], v[24:25], v[104:105]
	v_pk_add_f32 v[26:27], v[26:27], v[106:107]
	v_pk_add_f32 v[24:25], v[24:25], v[108:109]
	v_pk_add_f32 v[26:27], v[26:27], v[110:111]
	v_pk_add_f32 v[24:25], v[24:25], v[112:113]
	v_pk_add_f32 v[26:27], v[26:27], v[114:115]
	v_pk_add_f32 v[24:25], v[24:25], v[116:117]
	v_pk_add_f32 v[26:27], v[26:27], v[118:119]
	v_pk_add_f32 v[24:25], v[24:25], v[120:121]
	v_pk_add_f32 v[26:27], v[26:27], v[122:123]
	v_pk_add_f32 v[24:25], v[24:25], v[124:125]
	v_pk_add_f32 v[26:27], v[26:27], v[126:127]

.LBB0_93:
	v_add_co_u32_e32 v84, vcc, 0x400000, v46
	s_nop 1
	v_addc_co_u32_e32 v85, vcc, 0, v47, vcc
	v_add_co_u32_e32 v86, vcc, 0x800000, v46
	s_nop 1
	v_addc_co_u32_e32 v87, vcc, 0, v47, vcc
	v_add_co_u32_e32 v88, vcc, 0xc00000, v46
	s_nop 1
	v_addc_co_u32_e32 v89, vcc, 0, v47, vcc
	v_add_co_u32_e32 v90, vcc, 0x1000000, v46
	s_nop 1
	v_addc_co_u32_e32 v91, vcc, 0, v47, vcc
	v_add_co_u32_e32 v92, vcc, 0x1400000, v46
	s_nop 1
	v_addc_co_u32_e32 v93, vcc, 0, v47, vcc
	v_add_co_u32_e32 v94, vcc, 0x1800000, v46
	s_nop 1
	v_addc_co_u32_e32 v95, vcc, 0, v47, vcc
	v_add_co_u32_e32 v96, vcc, 0x1c00000, v46
	s_nop 1
	v_addc_co_u32_e32 v97, vcc, 0, v47, vcc
	global_load_dwordx4 v[28:31], v[46:47], off offset:2048
	global_load_dwordx4 v[100:103], v[84:85], off offset:2048
	global_load_dwordx4 v[104:107], v[86:87], off offset:2048
	global_load_dwordx4 v[108:111], v[88:89], off offset:2048
	global_load_dwordx4 v[112:115], v[90:91], off offset:2048
	global_load_dwordx4 v[116:119], v[92:93], off offset:2048
	global_load_dwordx4 v[120:123], v[94:95], off offset:2048
	global_load_dwordx4 v[124:127], v[96:97], off offset:2048
	s_waitcnt vmcnt(0)
	v_pk_add_f32 v[28:29], v[28:29], v[100:101]
	v_pk_add_f32 v[30:31], v[30:31], v[102:103]
	v_pk_add_f32 v[28:29], v[28:29], v[104:105]
	v_pk_add_f32 v[30:31], v[30:31], v[106:107]
	v_pk_add_f32 v[28:29], v[28:29], v[108:109]
	v_pk_add_f32 v[30:31], v[30:31], v[110:111]
	v_pk_add_f32 v[28:29], v[28:29], v[112:113]
	v_pk_add_f32 v[30:31], v[30:31], v[114:115]
	v_pk_add_f32 v[28:29], v[28:29], v[116:117]
	v_pk_add_f32 v[30:31], v[30:31], v[118:119]
	v_pk_add_f32 v[28:29], v[28:29], v[120:121]
	v_pk_add_f32 v[30:31], v[30:31], v[122:123]
	v_pk_add_f32 v[28:29], v[28:29], v[124:125]
	v_pk_add_f32 v[30:31], v[30:31], v[126:127]

.LBB0_97:
	v_add_co_u32_e32 v84, vcc, 0x400000, v46
	s_nop 1
	v_addc_co_u32_e32 v85, vcc, 0, v47, vcc
	v_add_co_u32_e32 v86, vcc, 0x800000, v46
	s_nop 1
	v_addc_co_u32_e32 v87, vcc, 0, v47, vcc
	v_add_co_u32_e32 v88, vcc, 0xc00000, v46
	s_nop 1
	v_addc_co_u32_e32 v89, vcc, 0, v47, vcc
	v_add_co_u32_e32 v90, vcc, 0x1000000, v46
	s_nop 1
	v_addc_co_u32_e32 v91, vcc, 0, v47, vcc
	v_add_co_u32_e32 v92, vcc, 0x1400000, v46
	s_nop 1
	v_addc_co_u32_e32 v93, vcc, 0, v47, vcc
	v_add_co_u32_e32 v94, vcc, 0x1800000, v46
	s_nop 1
	v_addc_co_u32_e32 v95, vcc, 0, v47, vcc
	v_add_co_u32_e32 v96, vcc, 0x1c00000, v46
	s_nop 1
	v_addc_co_u32_e32 v97, vcc, 0, v47, vcc
	global_load_dwordx4 v[32:35], v[46:47], off offset:3072
	global_load_dwordx4 v[100:103], v[84:85], off offset:3072
	global_load_dwordx4 v[104:107], v[86:87], off offset:3072
	global_load_dwordx4 v[108:111], v[88:89], off offset:3072
	global_load_dwordx4 v[112:115], v[90:91], off offset:3072
	global_load_dwordx4 v[116:119], v[92:93], off offset:3072
	global_load_dwordx4 v[120:123], v[94:95], off offset:3072
	global_load_dwordx4 v[124:127], v[96:97], off offset:3072
	s_waitcnt vmcnt(0)
	v_pk_add_f32 v[32:33], v[32:33], v[100:101]
	v_pk_add_f32 v[34:35], v[34:35], v[102:103]
	v_pk_add_f32 v[32:33], v[32:33], v[104:105]
	v_pk_add_f32 v[34:35], v[34:35], v[106:107]
	v_pk_add_f32 v[32:33], v[32:33], v[108:109]
	v_pk_add_f32 v[34:35], v[34:35], v[110:111]
	v_pk_add_f32 v[32:33], v[32:33], v[112:113]
	v_pk_add_f32 v[34:35], v[34:35], v[114:115]
	v_pk_add_f32 v[32:33], v[32:33], v[116:117]
	v_pk_add_f32 v[34:35], v[34:35], v[118:119]
	v_pk_add_f32 v[32:33], v[32:33], v[120:121]
	v_pk_add_f32 v[34:35], v[34:35], v[122:123]
	v_pk_add_f32 v[32:33], v[32:33], v[124:125]
	v_pk_add_f32 v[34:35], v[34:35], v[126:127]
	s_branch .LBB0_79

.LBB0_199:
	s_or_saveexec_b64 s[24:25], s[24:25]
	v_add_u32_e32 v24, 0xffffc000, v0
	v_mov_b32_e32 v25, v2
	v_lshlrev_b64 v[24:25], 12, v[24:25]
	v_lshl_add_u64 v[50:51], v[46:47], 0, v[24:25]
	s_xor_b64 exec, exec, s[24:25]
	s_cbranch_execz .LBB0_201
	v_add_co_u32_e32 v84, vcc, 0x400000, v50
	s_nop 1
	v_addc_co_u32_e32 v85, vcc, 0, v51, vcc
	v_add_co_u32_e32 v86, vcc, 0x800000, v50
	s_nop 1
	v_addc_co_u32_e32 v87, vcc, 0, v51, vcc
	v_add_co_u32_e32 v88, vcc, 0xc00000, v50
	s_nop 1
	v_addc_co_u32_e32 v89, vcc, 0, v51, vcc
	v_add_co_u32_e32 v90, vcc, 0x1000000, v50
	s_nop 1
	v_addc_co_u32_e32 v91, vcc, 0, v51, vcc
	v_add_co_u32_e32 v92, vcc, 0x1400000, v50
	s_nop 1
	v_addc_co_u32_e32 v93, vcc, 0, v51, vcc
	v_add_co_u32_e32 v94, vcc, 0x1800000, v50
	s_nop 1
	v_addc_co_u32_e32 v95, vcc, 0, v51, vcc
	v_add_co_u32_e32 v96, vcc, 0x1c00000, v50
	s_nop 1
	v_addc_co_u32_e32 v97, vcc, 0, v51, vcc
	global_load_dwordx4 v[20:23], v[50:51], off
	global_load_dwordx4 v[100:103], v[84:85], off
	global_load_dwordx4 v[104:107], v[86:87], off
	global_load_dwordx4 v[108:111], v[88:89], off
	global_load_dwordx4 v[112:115], v[90:91], off
	global_load_dwordx4 v[116:119], v[92:93], off
	global_load_dwordx4 v[120:123], v[94:95], off
	global_load_dwordx4 v[124:127], v[96:97], off
	s_waitcnt vmcnt(0)
	v_pk_add_f32 v[20:21], v[20:21], v[100:101]
	v_pk_add_f32 v[22:23], v[22:23], v[102:103]
	v_pk_add_f32 v[20:21], v[20:21], v[104:105]
	v_pk_add_f32 v[22:23], v[22:23], v[106:107]
	v_pk_add_f32 v[20:21], v[20:21], v[108:109]
	v_pk_add_f32 v[22:23], v[22:23], v[110:111]
	v_pk_add_f32 v[20:21], v[20:21], v[112:113]
	v_pk_add_f32 v[22:23], v[22:23], v[114:115]
	v_pk_add_f32 v[20:21], v[20:21], v[116:117]
	v_pk_add_f32 v[22:23], v[22:23], v[118:119]
	v_pk_add_f32 v[20:21], v[20:21], v[120:121]
	v_pk_add_f32 v[22:23], v[22:23], v[122:123]
	v_pk_add_f32 v[20:21], v[20:21], v[124:125]
	v_pk_add_f32 v[22:23], v[22:23], v[126:127]

.LBB0_204:
	v_add_co_u32_e32 v84, vcc, 0x400000, v50
	s_nop 1
	v_addc_co_u32_e32 v85, vcc, 0, v51, vcc
	v_add_co_u32_e32 v86, vcc, 0x800000, v50
	s_nop 1
	v_addc_co_u32_e32 v87, vcc, 0, v51, vcc
	v_add_co_u32_e32 v88, vcc, 0xc00000, v50
	s_nop 1
	v_addc_co_u32_e32 v89, vcc, 0, v51, vcc
	v_add_co_u32_e32 v90, vcc, 0x1000000, v50
	s_nop 1
	v_addc_co_u32_e32 v91, vcc, 0, v51, vcc
	v_add_co_u32_e32 v92, vcc, 0x1400000, v50
	s_nop 1
	v_addc_co_u32_e32 v93, vcc, 0, v51, vcc
	v_add_co_u32_e32 v94, vcc, 0x1800000, v50
	s_nop 1
	v_addc_co_u32_e32 v95, vcc, 0, v51, vcc
	v_add_co_u32_e32 v96, vcc, 0x1c00000, v50
	s_nop 1
	v_addc_co_u32_e32 v97, vcc, 0, v51, vcc
	global_load_dwordx4 v[24:27], v[50:51], off offset:1024
	global_load_dwordx4 v[100:103], v[84:85], off offset:1024
	global_load_dwordx4 v[104:107], v[86:87], off offset:1024
	global_load_dwordx4 v[108:111], v[88:89], off offset:1024
	global_load_dwordx4 v[112:115], v[90:91], off offset:1024
	global_load_dwordx4 v[116:119], v[92:93], off offset:1024
	global_load_dwordx4 v[120:123], v[94:95], off offset:1024
	global_load_dwordx4 v[124:127], v[96:97], off offset:1024
	s_waitcnt vmcnt(0)
	v_pk_add_f32 v[24:25], v[24:25], v[100:101]
	v_pk_add_f32 v[26:27], v[26:27], v[102:103]
	v_pk_add_f32 v[24:25], v[24:25], v[104:105]
	v_pk_add_f32 v[26:27], v[26:27], v[106:107]
	v_pk_add_f32 v[24:25], v[24:25], v[108:109]
	v_pk_add_f32 v[26:27], v[26:27], v[110:111]
	v_pk_add_f32 v[24:25], v[24:25], v[112:113]
	v_pk_add_f32 v[26:27], v[26:27], v[114:115]
	v_pk_add_f32 v[24:25], v[24:25], v[116:117]
	v_pk_add_f32 v[26:27], v[26:27], v[118:119]
	v_pk_add_f32 v[24:25], v[24:25], v[120:121]
	v_pk_add_f32 v[26:27], v[26:27], v[122:123]
	v_pk_add_f32 v[24:25], v[24:25], v[124:125]
	v_pk_add_f32 v[26:27], v[26:27], v[126:127]

.LBB0_208:
	v_add_co_u32_e32 v84, vcc, 0x400000, v50
	s_nop 1
	v_addc_co_u32_e32 v85, vcc, 0, v51, vcc
	v_add_co_u32_e32 v86, vcc, 0x800000, v50
	s_nop 1
	v_addc_co_u32_e32 v87, vcc, 0, v51, vcc
	v_add_co_u32_e32 v88, vcc, 0xc00000, v50
	s_nop 1
	v_addc_co_u32_e32 v89, vcc, 0, v51, vcc
	v_add_co_u32_e32 v90, vcc, 0x1000000, v50
	s_nop 1
	v_addc_co_u32_e32 v91, vcc, 0, v51, vcc
	v_add_co_u32_e32 v92, vcc, 0x1400000, v50
	s_nop 1
	v_addc_co_u32_e32 v93, vcc, 0, v51, vcc
	v_add_co_u32_e32 v94, vcc, 0x1800000, v50
	s_nop 1
	v_addc_co_u32_e32 v95, vcc, 0, v51, vcc
	v_add_co_u32_e32 v96, vcc, 0x1c00000, v50
	s_nop 1
	v_addc_co_u32_e32 v97, vcc, 0, v51, vcc
	global_load_dwordx4 v[28:31], v[50:51], off offset:2048
	global_load_dwordx4 v[100:103], v[84:85], off offset:2048
	global_load_dwordx4 v[104:107], v[86:87], off offset:2048
	global_load_dwordx4 v[108:111], v[88:89], off offset:2048
	global_load_dwordx4 v[112:115], v[90:91], off offset:2048
	global_load_dwordx4 v[116:119], v[92:93], off offset:2048
	global_load_dwordx4 v[120:123], v[94:95], off offset:2048
	global_load_dwordx4 v[124:127], v[96:97], off offset:2048
	s_waitcnt vmcnt(0)
	v_pk_add_f32 v[28:29], v[28:29], v[100:101]
	v_pk_add_f32 v[30:31], v[30:31], v[102:103]
	v_pk_add_f32 v[28:29], v[28:29], v[104:105]
	v_pk_add_f32 v[30:31], v[30:31], v[106:107]
	v_pk_add_f32 v[28:29], v[28:29], v[108:109]
	v_pk_add_f32 v[30:31], v[30:31], v[110:111]
	v_pk_add_f32 v[28:29], v[28:29], v[112:113]
	v_pk_add_f32 v[30:31], v[30:31], v[114:115]
	v_pk_add_f32 v[28:29], v[28:29], v[116:117]
	v_pk_add_f32 v[30:31], v[30:31], v[118:119]
	v_pk_add_f32 v[28:29], v[28:29], v[120:121]
	v_pk_add_f32 v[30:31], v[30:31], v[122:123]
	v_pk_add_f32 v[28:29], v[28:29], v[124:125]
	v_pk_add_f32 v[30:31], v[30:31], v[126:127]

.LBB0_212:
	v_add_co_u32_e32 v84, vcc, 0x400000, v50
	s_nop 1
	v_addc_co_u32_e32 v85, vcc, 0, v51, vcc
	v_add_co_u32_e32 v86, vcc, 0x800000, v50
	s_nop 1
	v_addc_co_u32_e32 v87, vcc, 0, v51, vcc
	v_add_co_u32_e32 v88, vcc, 0xc00000, v50
	s_nop 1
	v_addc_co_u32_e32 v89, vcc, 0, v51, vcc
	v_add_co_u32_e32 v90, vcc, 0x1000000, v50
	s_nop 1
	v_addc_co_u32_e32 v91, vcc, 0, v51, vcc
	v_add_co_u32_e32 v92, vcc, 0x1400000, v50
	s_nop 1
	v_addc_co_u32_e32 v93, vcc, 0, v51, vcc
	v_add_co_u32_e32 v94, vcc, 0x1800000, v50
	s_nop 1
	v_addc_co_u32_e32 v95, vcc, 0, v51, vcc
	v_add_co_u32_e32 v96, vcc, 0x1c00000, v50
	s_nop 1
	v_addc_co_u32_e32 v97, vcc, 0, v51, vcc
	global_load_dwordx4 v[32:35], v[50:51], off offset:3072
	global_load_dwordx4 v[100:103], v[84:85], off offset:3072
	global_load_dwordx4 v[104:107], v[86:87], off offset:3072
	global_load_dwordx4 v[108:111], v[88:89], off offset:3072
	global_load_dwordx4 v[112:115], v[90:91], off offset:3072
	global_load_dwordx4 v[116:119], v[92:93], off offset:3072
	global_load_dwordx4 v[120:123], v[94:95], off offset:3072
	global_load_dwordx4 v[124:127], v[96:97], off offset:3072
	s_waitcnt vmcnt(0)
	v_pk_add_f32 v[32:33], v[32:33], v[100:101]
	v_pk_add_f32 v[34:35], v[34:35], v[102:103]
	v_pk_add_f32 v[32:33], v[32:33], v[104:105]
	v_pk_add_f32 v[34:35], v[34:35], v[106:107]
	v_pk_add_f32 v[32:33], v[32:33], v[108:109]
	v_pk_add_f32 v[34:35], v[34:35], v[110:111]
	v_pk_add_f32 v[32:33], v[32:33], v[112:113]
	v_pk_add_f32 v[34:35], v[34:35], v[114:115]
	v_pk_add_f32 v[32:33], v[32:33], v[116:117]
	v_pk_add_f32 v[34:35], v[34:35], v[118:119]
	v_pk_add_f32 v[32:33], v[32:33], v[120:121]
	v_pk_add_f32 v[34:35], v[34:35], v[122:123]
	v_pk_add_f32 v[32:33], v[32:33], v[124:125]
	v_pk_add_f32 v[34:35], v[34:35], v[126:127]
